# phase-0 x-row loop: DeltaNet gate activations (softplus/sigmoid) evaluated once per 8 rows across all 64 lanes instead of per row on 8 lanes
# baseline (speedup 1.0000x reference)
.LBB0_129:
	s_or_b64 exec, exec, s[0:1]
	v_ashrrev_i32_e32 v2, 3, v130
	v_readlane_b32 s16, v254, 0
	v_ashrrev_i32_e32 v3, 31, v2
	v_readlane_b32 s18, v254, 2
	v_readlane_b32 s19, v254, 3
	v_readlane_b32 s20, v254, 4
	v_readlane_b32 s21, v254, 5
	v_and_b32_e32 v6, 7, v130
	v_lshl_add_u64 v[4:5], v[2:3], 2, s[18:19]
	s_movk_i32 s0, 0x2c20
	v_mov_b64_e32 v[8:9], s[20:21]
	global_load_dword v1, v[4:5], off
	v_mad_i64_i32 v[4:5], s[4:5], v2, s0, v[8:9]
	v_lshlrev_b32_e32 v134, 2, v6
	v_mov_b32_e32 v135, 0
	v_lshl_add_u64 v[4:5], v[4:5], 0, v[134:135]
	v_add_co_u32_e32 v4, vcc, 0x2000, v4
	s_movk_i32 s1, 0x2000
	s_nop 0
	v_addc_co_u32_e32 v5, vcc, 0, v5, vcc
	global_load_dword v3, v[4:5], off offset:1024
	v_add_u32_e32 v4, 0x100, v130
	v_ashrrev_i32_e32 v4, 3, v4
	v_ashrrev_i32_e32 v5, 31, v4
	v_lshl_add_u64 v[6:7], v[4:5], 2, s[18:19]
	global_load_dword v5, v[6:7], off
	v_mad_i64_i32 v[6:7], s[4:5], v4, s0, v[8:9]
	v_lshl_add_u64 v[6:7], v[6:7], 0, v[134:135]
	v_add_co_u32_e32 v6, vcc, s1, v6
	v_readlane_b32 s17, v254, 1
	s_nop 0
	v_addc_co_u32_e32 v7, vcc, 0, v7, vcc
	global_load_dword v70, v[6:7], off offset:1024
	v_add_u32_e32 v6, 0x200, v130
	v_ashrrev_i32_e32 v6, 3, v6
	v_ashrrev_i32_e32 v7, 31, v6
	v_lshl_add_u64 v[10:11], v[6:7], 2, s[18:19]
	global_load_dword v7, v[10:11], off
	v_mad_i64_i32 v[10:11], s[4:5], v6, s0, v[8:9]
	v_lshl_add_u64 v[10:11], v[10:11], 0, v[134:135]
	v_add_co_u32_e32 v10, vcc, s1, v10
	v_readlane_b32 s22, v254, 6
	s_nop 0
	v_addc_co_u32_e32 v11, vcc, 0, v11, vcc
	global_load_dword v71, v[10:11], off offset:1024
	v_add_u32_e32 v10, 0x300, v130
	v_ashrrev_i32_e32 v10, 3, v10
	v_ashrrev_i32_e32 v11, 31, v10
	v_lshl_add_u64 v[12:13], v[10:11], 2, s[18:19]
	global_load_dword v11, v[12:13], off
	v_mad_i64_i32 v[12:13], s[4:5], v10, s0, v[8:9]
	v_lshl_add_u64 v[12:13], v[12:13], 0, v[134:135]
	v_add_co_u32_e32 v12, vcc, s1, v12
	v_readlane_b32 s23, v254, 7
	s_nop 0
	v_addc_co_u32_e32 v13, vcc, 0, v13, vcc
	global_load_dword v72, v[12:13], off offset:1024
	v_add_u32_e32 v12, 0x400, v130
	v_ashrrev_i32_e32 v12, 3, v12
	v_ashrrev_i32_e32 v13, 31, v12
	v_lshl_add_u64 v[14:15], v[12:13], 2, s[18:19]
	global_load_dword v13, v[14:15], off
	v_mad_i64_i32 v[14:15], s[4:5], v12, s0, v[8:9]
	v_lshl_add_u64 v[14:15], v[14:15], 0, v[134:135]
	v_add_co_u32_e32 v14, vcc, s1, v14
	v_readlane_b32 s24, v254, 8
	s_nop 0
	v_addc_co_u32_e32 v15, vcc, 0, v15, vcc
	global_load_dword v73, v[14:15], off offset:1024
	v_add_u32_e32 v14, 0x500, v130
	v_ashrrev_i32_e32 v14, 3, v14
	v_ashrrev_i32_e32 v15, 31, v14
	v_lshl_add_u64 v[16:17], v[14:15], 2, s[18:19]
	global_load_dword v15, v[16:17], off
	v_mad_i64_i32 v[16:17], s[4:5], v14, s0, v[8:9]
	v_lshl_add_u64 v[16:17], v[16:17], 0, v[134:135]
	v_add_co_u32_e32 v16, vcc, s1, v16
	v_readlane_b32 s25, v254, 9
	s_nop 0
	v_addc_co_u32_e32 v17, vcc, 0, v17, vcc
	global_load_dword v74, v[16:17], off offset:1024
	v_add_u32_e32 v16, 0x600, v130
	v_ashrrev_i32_e32 v16, 3, v16
	v_ashrrev_i32_e32 v17, 31, v16
	v_lshl_add_u64 v[18:19], v[16:17], 2, s[18:19]
	global_load_dword v17, v[18:19], off
	v_mad_i64_i32 v[18:19], s[4:5], v16, s0, v[8:9]
	v_lshl_add_u64 v[18:19], v[18:19], 0, v[134:135]
	v_add_co_u32_e32 v18, vcc, s1, v18
	s_waitcnt vmcnt(11)
	v_mul_f32_e32 v1, v1, v3
	v_addc_co_u32_e32 v19, vcc, 0, v19, vcc
	global_load_dword v75, v[18:19], off offset:1024
	v_add_u32_e32 v18, 0x700, v130
	v_ashrrev_i32_e32 v18, 3, v18
	v_ashrrev_i32_e32 v19, 31, v18
	v_lshl_add_u64 v[20:21], v[18:19], 2, s[18:19]
	global_load_dword v19, v[20:21], off
	v_mad_i64_i32 v[20:21], s[4:5], v18, s0, v[8:9]
	v_lshl_add_u64 v[20:21], v[20:21], 0, v[134:135]
	v_add_co_u32_e32 v20, vcc, s1, v20
	s_waitcnt vmcnt(11)
	v_mul_f32_e32 v3, v5, v70
	v_addc_co_u32_e32 v21, vcc, 0, v21, vcc
	global_load_dword v76, v[20:21], off offset:1024
	v_add_u32_e32 v20, 0x800, v130
	v_ashrrev_i32_e32 v20, 3, v20
	v_ashrrev_i32_e32 v21, 31, v20
	v_lshl_add_u64 v[22:23], v[20:21], 2, s[18:19]
	global_load_dword v21, v[22:23], off
	v_mad_i64_i32 v[22:23], s[4:5], v20, s0, v[8:9]
	v_lshl_add_u64 v[22:23], v[22:23], 0, v[134:135]
	v_add_co_u32_e32 v22, vcc, s1, v22
	s_waitcnt vmcnt(11)
	v_mul_f32_e32 v5, v7, v71
	v_addc_co_u32_e32 v23, vcc, 0, v23, vcc
	global_load_dword v77, v[22:23], off offset:1024
	v_add_u32_e32 v22, 0x900, v130
	v_ashrrev_i32_e32 v22, 3, v22
	v_ashrrev_i32_e32 v23, 31, v22
	v_lshl_add_u64 v[24:25], v[22:23], 2, s[18:19]
	global_load_dword v23, v[24:25], off
	v_mad_i64_i32 v[24:25], s[4:5], v22, s0, v[8:9]
	v_lshl_add_u64 v[24:25], v[24:25], 0, v[134:135]
	v_add_co_u32_e32 v24, vcc, s1, v24
	s_waitcnt vmcnt(11)
	v_mul_f32_e32 v7, v11, v72
	v_addc_co_u32_e32 v25, vcc, 0, v25, vcc
	global_load_dword v78, v[24:25], off offset:1024
	v_add_u32_e32 v24, 0xa00, v130
	v_ashrrev_i32_e32 v24, 3, v24
	v_ashrrev_i32_e32 v25, 31, v24
	v_lshl_add_u64 v[26:27], v[24:25], 2, s[18:19]
	global_load_dword v25, v[26:27], off
	v_mad_i64_i32 v[26:27], s[4:5], v24, s0, v[8:9]
	v_lshl_add_u64 v[26:27], v[26:27], 0, v[134:135]
	v_add_co_u32_e32 v26, vcc, s1, v26
	v_readlane_b32 s26, v254, 10
	s_nop 0
	v_addc_co_u32_e32 v27, vcc, 0, v27, vcc
	global_load_dword v79, v[26:27], off offset:1024
	v_add_u32_e32 v26, 0xb00, v130
	v_ashrrev_i32_e32 v26, 3, v26
	v_ashrrev_i32_e32 v27, 31, v26
	v_lshl_add_u64 v[28:29], v[26:27], 2, s[18:19]
	global_load_dword v27, v[28:29], off
	v_mad_i64_i32 v[28:29], s[4:5], v26, s0, v[8:9]
	v_lshl_add_u64 v[28:29], v[28:29], 0, v[134:135]
	v_add_co_u32_e32 v28, vcc, s1, v28
	s_waitcnt vmcnt(11)
	v_mul_f32_e32 v11, v15, v74
	v_addc_co_u32_e32 v29, vcc, 0, v29, vcc
	global_load_dword v80, v[28:29], off offset:1024
	v_add_u32_e32 v28, 0xc00, v130
	v_ashrrev_i32_e32 v28, 3, v28
	v_ashrrev_i32_e32 v29, 31, v28
	v_lshl_add_u64 v[30:31], v[28:29], 2, s[18:19]
	global_load_dword v29, v[30:31], off
	v_mad_i64_i32 v[30:31], s[4:5], v28, s0, v[8:9]
	v_lshl_add_u64 v[30:31], v[30:31], 0, v[134:135]
	v_add_co_u32_e32 v30, vcc, s1, v30
	v_readlane_b32 s27, v254, 11
	s_nop 0
	v_addc_co_u32_e32 v31, vcc, 0, v31, vcc
	global_load_dword v81, v[30:31], off offset:1024
	v_add_u32_e32 v30, 0xd00, v130
	v_ashrrev_i32_e32 v30, 3, v30
	v_ashrrev_i32_e32 v31, 31, v30
	v_lshl_add_u64 v[32:33], v[30:31], 2, s[18:19]
	global_load_dword v31, v[32:33], off
	v_mad_i64_i32 v[32:33], s[4:5], v30, s0, v[8:9]
	v_lshl_add_u64 v[32:33], v[32:33], 0, v[134:135]
	v_add_co_u32_e32 v32, vcc, s1, v32
	s_waitcnt vmcnt(11)
	v_mul_f32_e32 v15, v19, v76
	v_addc_co_u32_e32 v33, vcc, 0, v33, vcc
	global_load_dword v82, v[32:33], off offset:1024
	v_add_u32_e32 v32, 0xe00, v130
	v_ashrrev_i32_e32 v32, 3, v32
	v_ashrrev_i32_e32 v33, 31, v32
	v_lshl_add_u64 v[34:35], v[32:33], 2, s[18:19]
	global_load_dword v33, v[34:35], off
	v_mad_i64_i32 v[34:35], s[4:5], v32, s0, v[8:9]
	v_lshl_add_u64 v[34:35], v[34:35], 0, v[134:135]
	v_add_co_u32_e32 v34, vcc, s1, v34
	v_readlane_b32 s28, v254, 12
	s_nop 0
	v_addc_co_u32_e32 v35, vcc, 0, v35, vcc
	global_load_dword v83, v[34:35], off offset:1024
	v_add_u32_e32 v34, 0xf00, v130
	v_ashrrev_i32_e32 v34, 3, v34
	v_ashrrev_i32_e32 v35, 31, v34
	v_lshl_add_u64 v[36:37], v[34:35], 2, s[18:19]
	global_load_dword v35, v[36:37], off
	v_mad_i64_i32 v[36:37], s[4:5], v34, s0, v[8:9]
	v_lshl_add_u64 v[36:37], v[36:37], 0, v[134:135]
	v_add_co_u32_e32 v36, vcc, s1, v36
	s_waitcnt vmcnt(11)
	v_mul_f32_e32 v19, v23, v78
	v_addc_co_u32_e32 v37, vcc, 0, v37, vcc
	global_load_dword v84, v[36:37], off offset:1024
	v_add_u32_e32 v36, 0x1000, v130
	v_ashrrev_i32_e32 v36, 3, v36
	v_ashrrev_i32_e32 v37, 31, v36
	v_lshl_add_u64 v[38:39], v[36:37], 2, s[18:19]
	global_load_dword v37, v[38:39], off
	v_mad_i64_i32 v[38:39], s[4:5], v36, s0, v[8:9]
	v_lshl_add_u64 v[38:39], v[38:39], 0, v[134:135]
	v_add_co_u32_e32 v38, vcc, s1, v38
	v_readlane_b32 s29, v254, 13
	s_nop 0
	v_addc_co_u32_e32 v39, vcc, 0, v39, vcc
	global_load_dword v85, v[38:39], off offset:1024
	v_add_u32_e32 v38, 0x1100, v130
	v_ashrrev_i32_e32 v38, 3, v38
	v_ashrrev_i32_e32 v39, 31, v38
	v_lshl_add_u64 v[40:41], v[38:39], 2, s[18:19]
	global_load_dword v39, v[40:41], off
	v_mad_i64_i32 v[40:41], s[4:5], v38, s0, v[8:9]
	v_lshl_add_u64 v[40:41], v[40:41], 0, v[134:135]
	v_add_co_u32_e32 v40, vcc, s1, v40
	s_waitcnt vmcnt(11)
	v_mul_f32_e32 v23, v27, v80
	v_addc_co_u32_e32 v41, vcc, 0, v41, vcc
	global_load_dword v86, v[40:41], off offset:1024
	v_add_u32_e32 v40, 0x1200, v130
	v_ashrrev_i32_e32 v40, 3, v40
	v_ashrrev_i32_e32 v41, 31, v40
	v_lshl_add_u64 v[42:43], v[40:41], 2, s[18:19]
	global_load_dword v41, v[42:43], off
	v_mad_i64_i32 v[42:43], s[4:5], v40, s0, v[8:9]
	v_lshl_add_u64 v[42:43], v[42:43], 0, v[134:135]
	v_add_co_u32_e32 v42, vcc, s1, v42
	v_readlane_b32 s30, v254, 14
	s_nop 0
	v_addc_co_u32_e32 v43, vcc, 0, v43, vcc
	global_load_dword v87, v[42:43], off offset:1024
	v_add_u32_e32 v42, 0x1300, v130
	v_ashrrev_i32_e32 v42, 3, v42
	v_ashrrev_i32_e32 v43, 31, v42
	v_lshl_add_u64 v[44:45], v[42:43], 2, s[18:19]
	global_load_dword v43, v[44:45], off
	v_mad_i64_i32 v[44:45], s[4:5], v42, s0, v[8:9]
	v_lshl_add_u64 v[44:45], v[44:45], 0, v[134:135]
	v_add_co_u32_e32 v44, vcc, s1, v44
	s_waitcnt vmcnt(11)
	v_mul_f32_e32 v27, v31, v82
	v_addc_co_u32_e32 v45, vcc, 0, v45, vcc
	global_load_dword v88, v[44:45], off offset:1024
	v_add_u32_e32 v44, 0x1400, v130
	v_ashrrev_i32_e32 v44, 3, v44
	v_ashrrev_i32_e32 v45, 31, v44
	v_lshl_add_u64 v[46:47], v[44:45], 2, s[18:19]
	global_load_dword v45, v[46:47], off
	v_mad_i64_i32 v[46:47], s[4:5], v44, s0, v[8:9]
	v_lshl_add_u64 v[46:47], v[46:47], 0, v[134:135]
	v_add_co_u32_e32 v46, vcc, s1, v46
	v_readlane_b32 s31, v254, 15
	s_nop 0
	v_addc_co_u32_e32 v47, vcc, 0, v47, vcc
	global_load_dword v89, v[46:47], off offset:1024
	v_add_u32_e32 v46, 0x1500, v130
	v_ashrrev_i32_e32 v46, 3, v46
	v_ashrrev_i32_e32 v47, 31, v46
	v_lshl_add_u64 v[48:49], v[46:47], 2, s[18:19]
	global_load_dword v47, v[48:49], off
	v_mad_i64_i32 v[48:49], s[4:5], v46, s0, v[8:9]
	v_lshl_add_u64 v[48:49], v[48:49], 0, v[134:135]
	v_add_co_u32_e32 v48, vcc, s1, v48
	s_waitcnt vmcnt(11)
	v_mul_f32_e32 v31, v35, v84
	v_addc_co_u32_e32 v49, vcc, 0, v49, vcc
	global_load_dword v90, v[48:49], off offset:1024
	v_add_u32_e32 v48, 0x1600, v130
	v_ashrrev_i32_e32 v48, 3, v48
	v_ashrrev_i32_e32 v49, 31, v48
	v_lshl_add_u64 v[50:51], v[48:49], 2, s[18:19]
	global_load_dword v49, v[50:51], off
	v_mad_i64_i32 v[50:51], s[4:5], v48, s0, v[8:9]
	v_lshl_add_u64 v[50:51], v[50:51], 0, v[134:135]
	v_add_co_u32_e32 v50, vcc, s1, v50
	s_waitcnt vmcnt(9)
	v_mul_f32_e32 v35, v39, v86
	v_addc_co_u32_e32 v51, vcc, 0, v51, vcc
	global_load_dword v91, v[50:51], off offset:1024
	v_add_u32_e32 v50, 0x1700, v130
	v_ashrrev_i32_e32 v50, 3, v50
	v_ashrrev_i32_e32 v51, 31, v50
	v_lshl_add_u64 v[52:53], v[50:51], 2, s[18:19]
	global_load_dword v51, v[52:53], off
	v_mad_i64_i32 v[52:53], s[4:5], v50, s0, v[8:9]
	v_lshl_add_u64 v[52:53], v[52:53], 0, v[134:135]
	v_add_co_u32_e32 v52, vcc, s1, v52
	s_waitcnt vmcnt(7)
	v_mul_f32_e32 v39, v43, v88
	v_addc_co_u32_e32 v53, vcc, 0, v53, vcc
	global_load_dword v92, v[52:53], off offset:1024
	v_add_u32_e32 v52, 0x1800, v130
	v_ashrrev_i32_e32 v52, 3, v52
	v_ashrrev_i32_e32 v53, 31, v52
	v_lshl_add_u64 v[54:55], v[52:53], 2, s[18:19]
	global_load_dword v53, v[54:55], off
	v_mad_i64_i32 v[54:55], s[4:5], v52, s0, v[8:9]
	v_lshl_add_u64 v[54:55], v[54:55], 0, v[134:135]
	v_add_co_u32_e32 v54, vcc, s1, v54
	s_waitcnt vmcnt(5)
	v_mul_f32_e32 v43, v47, v90
	v_addc_co_u32_e32 v55, vcc, 0, v55, vcc
	global_load_dword v93, v[54:55], off offset:1024
	v_add_u32_e32 v54, 0x1900, v130
	v_ashrrev_i32_e32 v54, 3, v54
	v_ashrrev_i32_e32 v55, 31, v54
	v_lshl_add_u64 v[56:57], v[54:55], 2, s[18:19]
	global_load_dword v55, v[56:57], off
	v_mad_i64_i32 v[56:57], s[4:5], v54, s0, v[8:9]
	v_lshl_add_u64 v[56:57], v[56:57], 0, v[134:135]
	v_add_co_u32_e32 v56, vcc, s1, v56
	s_waitcnt vmcnt(3)
	v_mul_f32_e32 v47, v51, v92
	v_addc_co_u32_e32 v57, vcc, 0, v57, vcc
	global_load_dword v94, v[56:57], off offset:1024
	v_add_u32_e32 v56, 0x1a00, v130
	v_ashrrev_i32_e32 v56, 3, v56
	v_ashrrev_i32_e32 v57, 31, v56
	v_lshl_add_u64 v[58:59], v[56:57], 2, s[18:19]
	global_load_dword v57, v[58:59], off
	v_mad_i64_i32 v[58:59], s[4:5], v56, s0, v[8:9]
	v_lshl_add_u64 v[58:59], v[58:59], 0, v[134:135]
	v_add_co_u32_e32 v58, vcc, s1, v58
	s_waitcnt vmcnt(1)
	v_mul_f32_e32 v51, v55, v94
	v_addc_co_u32_e32 v59, vcc, 0, v59, vcc
	global_load_dword v95, v[58:59], off offset:1024
	v_add_u32_e32 v58, 0x1b00, v130
	v_ashrrev_i32_e32 v58, 3, v58
	v_ashrrev_i32_e32 v59, 31, v58
	v_lshl_add_u64 v[60:61], v[58:59], 2, s[18:19]
	global_load_dword v59, v[60:61], off
	v_mad_i64_i32 v[60:61], s[4:5], v58, s0, v[8:9]
	v_lshl_add_u64 v[60:61], v[60:61], 0, v[134:135]
	v_add_co_u32_e32 v60, vcc, s1, v60
	s_nop 1
	v_addc_co_u32_e32 v61, vcc, 0, v61, vcc
	global_load_dword v96, v[60:61], off offset:1024
	v_add_u32_e32 v60, 0x1c00, v130
	v_ashrrev_i32_e32 v60, 3, v60
	v_ashrrev_i32_e32 v61, 31, v60
	v_lshl_add_u64 v[62:63], v[60:61], 2, s[18:19]
	global_load_dword v61, v[62:63], off
	v_mad_i64_i32 v[62:63], s[4:5], v60, s0, v[8:9]
	v_lshl_add_u64 v[62:63], v[62:63], 0, v[134:135]
	v_add_co_u32_e32 v62, vcc, s1, v62
	s_waitcnt vmcnt(1)
	v_mul_f32_e32 v55, v59, v96
	v_addc_co_u32_e32 v63, vcc, 0, v63, vcc
	global_load_dword v97, v[62:63], off offset:1024
	v_add_u32_e32 v62, 0x1d00, v130
	v_ashrrev_i32_e32 v62, 3, v62
	v_ashrrev_i32_e32 v63, 31, v62
	v_lshl_add_u64 v[64:65], v[62:63], 2, s[18:19]
	global_load_dword v63, v[64:65], off
	v_mad_i64_i32 v[64:65], s[4:5], v62, s0, v[8:9]
	v_lshl_add_u64 v[64:65], v[64:65], 0, v[134:135]
	v_add_co_u32_e32 v64, vcc, s1, v64
	s_nop 1
	v_addc_co_u32_e32 v65, vcc, 0, v65, vcc
	global_load_dword v98, v[64:65], off offset:1024
	v_add_u32_e32 v64, 0x1e00, v130
	v_ashrrev_i32_e32 v64, 3, v64
	v_ashrrev_i32_e32 v65, 31, v64
	v_lshl_add_u64 v[66:67], v[64:65], 2, s[18:19]
	global_load_dword v65, v[66:67], off
	v_mad_i64_i32 v[66:67], s[4:5], v64, s0, v[8:9]
	v_lshl_add_u64 v[66:67], v[66:67], 0, v[134:135]
	v_add_co_u32_e32 v66, vcc, s1, v66
	s_waitcnt vmcnt(1)
	v_mul_f32_e32 v59, v63, v98
	v_addc_co_u32_e32 v67, vcc, 0, v67, vcc
	global_load_dword v99, v[66:67], off offset:1024
	v_add_u32_e32 v66, 0x1f00, v130
	v_ashrrev_i32_e32 v66, 3, v66
	v_mad_i64_i32 v[8:9], s[4:5], v66, s0, v[8:9]
	v_lshl_add_u64 v[8:9], v[8:9], 0, v[134:135]
	v_ashrrev_i32_e32 v67, 31, v66
	v_add_co_u32_e32 v8, vcc, s1, v8
	v_lshl_add_u64 v[68:69], v[66:67], 2, s[18:19]
	s_nop 0
	v_addc_co_u32_e32 v9, vcc, 0, v9, vcc
	global_load_dword v67, v[68:69], off
	v_lshlrev_b32_e32 v63, 12, v130
	global_load_dword v8, v[8:9], off offset:1024
	v_and_b32_e32 v63, 0x7000, v63
	v_lshl_add_u32 v2, v2, 2, v63
	ds_write_b32 v2, v1
	v_lshl_add_u32 v1, v4, 2, v63
	ds_write_b32 v1, v3
	v_lshl_add_u32 v1, v6, 2, v63
	ds_write_b32 v1, v5
	v_lshl_add_u32 v1, v10, 2, v63
	v_mul_f32_e32 v9, v13, v73
	ds_write_b32 v1, v7
	v_lshl_add_u32 v1, v12, 2, v63
	ds_write_b32 v1, v9
	v_lshl_add_u32 v1, v14, 2, v63
	v_mul_f32_e32 v13, v17, v75
	ds_write_b32 v1, v11
	v_lshl_add_u32 v1, v16, 2, v63
	ds_write_b32 v1, v13
	v_lshl_add_u32 v1, v18, 2, v63
	v_mul_f32_e32 v17, v21, v77
	ds_write_b32 v1, v15
	v_lshl_add_u32 v1, v20, 2, v63
	ds_write_b32 v1, v17
	v_lshl_add_u32 v1, v22, 2, v63
	v_mul_f32_e32 v21, v25, v79
	ds_write_b32 v1, v19
	v_lshl_add_u32 v1, v24, 2, v63
	ds_write_b32 v1, v21
	v_lshl_add_u32 v1, v26, 2, v63
	v_mul_f32_e32 v25, v29, v81
	ds_write_b32 v1, v23
	v_lshl_add_u32 v1, v28, 2, v63
	ds_write_b32 v1, v25
	v_lshl_add_u32 v1, v30, 2, v63
	v_mul_f32_e32 v29, v33, v83
	ds_write_b32 v1, v27
	v_lshl_add_u32 v1, v32, 2, v63
	ds_write_b32 v1, v29
	v_lshl_add_u32 v1, v34, 2, v63
	v_mul_f32_e32 v33, v37, v85
	ds_write_b32 v1, v31
	v_lshl_add_u32 v1, v36, 2, v63
	ds_write_b32 v1, v33
	v_lshl_add_u32 v1, v38, 2, v63
	v_mul_f32_e32 v37, v41, v87
	ds_write_b32 v1, v35
	v_lshl_add_u32 v1, v40, 2, v63
	ds_write_b32 v1, v37
	v_lshl_add_u32 v1, v42, 2, v63
	v_mul_f32_e32 v41, v45, v89
	ds_write_b32 v1, v39
	v_lshl_add_u32 v1, v44, 2, v63
	ds_write_b32 v1, v41
	v_lshl_add_u32 v1, v46, 2, v63
	v_mul_f32_e32 v45, v49, v91
	ds_write_b32 v1, v43
	v_lshl_add_u32 v1, v48, 2, v63
	ds_write_b32 v1, v45
	v_lshl_add_u32 v1, v50, 2, v63
	v_mul_f32_e32 v49, v53, v93
	ds_write_b32 v1, v47
	v_lshl_add_u32 v1, v52, 2, v63
	ds_write_b32 v1, v49
	v_lshl_add_u32 v1, v54, 2, v63
	v_mul_f32_e32 v53, v57, v95
	ds_write_b32 v1, v51
	v_lshl_add_u32 v1, v56, 2, v63
	ds_write_b32 v1, v53
	v_lshl_add_u32 v1, v58, 2, v63
	v_mul_f32_e32 v57, v61, v97
	ds_write_b32 v1, v55
	v_lshl_add_u32 v1, v60, 2, v63
	ds_write_b32 v1, v57
	v_lshl_add_u32 v1, v62, 2, v63
	s_waitcnt vmcnt(2)
	v_mul_f32_e32 v61, v65, v99
	ds_write_b32 v1, v59
	v_lshl_add_u32 v1, v64, 2, v63
	s_mov_b32 s0, 0x10000
	ds_write_b32 v1, v61
	v_lshl_add_u32 v1, v66, 2, v63
	s_waitcnt vmcnt(0)
	v_mul_f32_e32 v8, v67, v8
	v_cmp_gt_i32_e32 vcc, s0, v162
	ds_write_b32 v1, v8
	s_waitcnt lgkmcnt(0)
	s_barrier
	s_and_saveexec_b64 s[16:17], vcc
	s_cbranch_execz .LBB0_142
	v_ashrrev_i32_e32 v163, 31, v162
	v_readlane_b32 s36, v254, 0
	v_lshlrev_b64 v[2:3], 12, v[162:163]
	v_readlane_b32 s37, v254, 1
	v_lshlrev_b32_e32 v134, 4, v132
	v_mbcnt_lo_u32_b32 v1, -1, 0
	v_lshl_add_u64 v[2:3], s[36:37], 0, v[2:3]
	v_lshl_add_u64 v[2:3], v[2:3], 0, v[134:135]
	global_load_dwordx4 v[158:161], v[2:3], off
	global_load_dwordx4 v[146:149], v[2:3], off offset:1024
	global_load_dwordx4 v[150:153], v[2:3], off offset:2048
	global_load_dwordx4 v[154:157], v[2:3], off offset:3072
	v_mbcnt_hi_u32_b32 v2, -1, v1
	v_and_b32_e32 v1, 64, v2
	v_add_u32_e32 v3, 64, v1
	v_xor_b32_e32 v1, 32, v2
	v_cmp_lt_i32_e32 vcc, v1, v3
	v_xor_b32_e32 v4, 16, v2
	v_readlane_b32 s40, v254, 4
	v_cndmask_b32_e32 v1, v2, v1, vcc
	v_cmp_lt_i32_e32 vcc, v4, v3
	v_readlane_b32 s41, v254, 5
	v_readlane_b32 s42, v254, 6
	v_cndmask_b32_e32 v4, v2, v4, vcc
	v_lshlrev_b32_e32 v178, 2, v4
	v_xor_b32_e32 v4, 8, v2
	v_cmp_lt_i32_e32 vcc, v4, v3
	v_readlane_b32 s43, v254, 7
	v_readlane_b32 s44, v254, 8
	v_cndmask_b32_e32 v4, v2, v4, vcc
	v_lshlrev_b32_e32 v179, 2, v4
	v_xor_b32_e32 v4, 4, v2
	v_cmp_lt_i32_e32 vcc, v4, v3
	v_readlane_b32 s45, v254, 9
	v_readlane_b32 s46, v254, 10
	v_cndmask_b32_e32 v4, v2, v4, vcc
	v_lshlrev_b32_e32 v180, 2, v4
	v_xor_b32_e32 v4, 2, v2
	v_cmp_lt_i32_e32 vcc, v4, v3
	v_readlane_b32 s47, v254, 11
	v_readlane_b32 s48, v254, 12
	v_cndmask_b32_e32 v4, v2, v4, vcc
	v_lshlrev_b32_e32 v181, 2, v4
	v_xor_b32_e32 v4, 1, v2
	v_cmp_lt_i32_e32 vcc, v4, v3
	v_readlane_b32 s49, v254, 13
	v_readlane_b32 s50, v254, 14
	v_cndmask_b32_e32 v2, v2, v4, vcc
	v_lshlrev_b32_e32 v182, 2, v2
	v_and_b32_e32 v2, 1, v130
	v_cmp_eq_u32_e64 s[0:1], 0, v2
	v_and_b32_e32 v2, 2, v130
	v_cmp_eq_u32_e64 s[4:5], 0, v2
	v_and_b32_e32 v2, 4, v130
	v_cmp_eq_u32_e64 s[6:7], 0, v2
	ds_read_b128 v[2:5], v134
	ds_read_b128 v[6:9], v134 offset:1024
	ds_read_b128 v[10:13], v134 offset:4096
	ds_read_b128 v[14:17], v134 offset:5120
	ds_read_b128 v[18:21], v134 offset:8192
	ds_read_b128 v[22:25], v134 offset:9216
	ds_read_b128 v[26:29], v134 offset:12288
	ds_read_b128 v[30:33], v134 offset:13312
	ds_read_b128 v[34:37], v134 offset:16384
	ds_read_b128 v[38:41], v134 offset:17408
	ds_read_b128 v[42:45], v134 offset:20480
	ds_read_b128 v[46:49], v134 offset:21504
	ds_read_b128 v[50:53], v134 offset:24576
	ds_read_b128 v[54:57], v134 offset:25600
	ds_read_b128 v[58:61], v134 offset:28672
	ds_read_b128 v[62:65], v134 offset:29696
	ds_read_b128 v[66:69], v134 offset:2048
	ds_read_b128 v[70:73], v134 offset:3072
	ds_read_b128 v[74:77], v134 offset:6144
	ds_read_b128 v[78:81], v134 offset:7168
	ds_read_b128 v[82:85], v134 offset:10240
	ds_read_b128 v[86:89], v134 offset:11264
	ds_read_b128 v[90:93], v134 offset:14336
	ds_read_b128 v[94:97], v134 offset:15360
	ds_read_b128 v[98:101], v134 offset:18432
	ds_read_b128 v[102:105], v134 offset:19456
	ds_read_b128 v[106:109], v134 offset:22528
	ds_read_b128 v[110:113], v134 offset:23552
	ds_read_b128 v[114:117], v134 offset:26624
	ds_read_b128 v[118:121], v134 offset:27648
	ds_read_b128 v[122:125], v134 offset:30720
	ds_read_b128 v[126:129], v134 offset:31744
	v_readlane_b32 s51, v254, 15
	v_lshlrev_b32_e32 v130, 2, v130
	v_readlane_b32 s40, v254, 16
	v_readlane_b32 s38, v254, 2
	v_readlane_b32 s39, v254, 3
	v_and_b32_e32 v130, 12, v130
	v_mov_b32_e32 v131, v135
	v_readlane_b32 s41, v254, 17
	v_readlane_b32 s42, v254, 18
	v_readlane_b32 s43, v254, 19
	v_readlane_b32 s44, v254, 20
	v_lshl_add_u64 v[168:169], s[36:37], 0, v[134:135]
	v_mov_b64_e32 v[134:135], 0x36b00000
	s_ashr_i32 s3, s2, 31
	v_lshlrev_b64 v[172:173], 4, v[162:163]
	v_lshlrev_b64 v[174:175], 11, v[162:163]
	v_lshlrev_b32_e32 v1, 2, v1
	v_cmp_eq_u32_e64 s[8:9], 0, v132
	v_cmp_gt_u32_e64 s[10:11], 8, v132
	v_cmp_lt_u32_e64 s[12:13], 3, v132
	v_lshl_add_u64 v[164:165], s[42:43], 0, v[130:131]
	v_lshl_add_u64 v[166:167], s[40:41], 0, v[130:131]
	v_lshl_add_u64 v[170:171], v[162:163], 2, v[134:135]
	s_lshl_b64 s[18:19], s[2:3], 2
	v_or_b32_e32 v172, v172, v130
	s_lshl_b64 s[20:21], s[2:3], 4
	v_lshl_or_b32 v174, v132, 3, v174
	s_lshl_b64 s[22:23], s[2:3], 11
	s_mov_b64 s[24:25], 0
	s_mov_b32 s3, 0xffff
	v_mov_b32_e32 v163, 0x358637bd
	s_mov_b32 s33, 0x800000
	s_mov_b32 s34, 0xbfb8aa3b
	s_mov_b32 s35, 0x42ce8ed0
	s_mov_b32 s36, 0xc2b17218
	s_mov_b32 s37, 0x7f800000
	s_mov_b32 s38, 0x41a00000
	s_mov_b32 s39, 0x3fb8aa3b
	s_mov_b32 s40, 0xc2ce8ed0
	s_mov_b32 s41, 0x42b17218
	s_mov_b32 s42, 0x3f2aaaab
	v_mov_b32_e32 v183, 0x3ecc95a3
	s_mov_b32 s43, 0x3f317218
	s_mov_b32 s44, 0x33800000
	v_mov_b32_e32 v184, 0x7f800000
	v_mov_b32_e32 v176, 0x3f317218
	v_readlane_b32 s45, v254, 21
	v_readlane_b32 s46, v254, 22
	v_readlane_b32 s47, v254, 23
	v_readlane_b32 s48, v254, 24
	v_readlane_b32 s49, v254, 25
	v_readlane_b32 s50, v254, 26
	v_readlane_b32 s51, v254, 27
	v_readlane_b32 s52, v254, 28
	v_readlane_b32 s53, v254, 29
	v_readlane_b32 s54, v254, 30
	v_readlane_b32 s55, v254, 31
	global_load_dword v252, v[164:165], off
	global_load_dword v253, v[166:167], off
	v_add_u32_e32 v228, s2, v162
	v_min_i32_e32 v228, 0xffff, v228
	v_ashrrev_i32_e32 v229, 31, v228
	v_lshlrev_b64 v[228:229], 12, v[228:229]
	v_lshl_add_u64 v[228:229], v[168:169], 0, v[228:229]
	global_load_dwordx4 v[142:145], v[228:229], off
	global_load_dwordx4 v[138:141], v[228:229], off offset:1024
	global_load_dwordx4 v[134:137], v[228:229], off offset:2048
	global_load_dwordx4 v[130:133], v[228:229], off offset:3072
	s_waitcnt vmcnt(0)
	s_mov_b32 s32, 0
	v_mbcnt_lo_u32_b32 v251, -1, 0
	v_mbcnt_hi_u32_b32 v251, -1, v251
	v_and_b32_e32 v248, 4, v251
	v_cmp_ne_u32_e64 s[62:63], 0, v248
	v_lshrrev_b32_e32 v251, 3, v251
	v_sub_u32_e32 v248, 7, v251
	v_mul_lo_u32 v246, v248, s20
	v_mov_b32_e32 v247, 0
	v_mov_b32_e32 v250, 0
	s_mov_b32 s61, 0
	s_branch .LBB0_134

.LBB0_132:
	s_or_b64 exec, exec, s[28:29]
	v_lshl_add_u64 v[146:147], v[172:173], 0, v[146:147]
	v_sub_co_u32_e32 v146, vcc, v146, v246
	s_nop 1
	v_subb_co_u32_e32 v147, vcc, v147, v247, vcc
	v_lshl_add_u64 v[146:147], s[92:93], 0, v[146:147]
	global_store_dword v[146:147], v149, off

.LBB0_136:
	s_or_b64 exec, exec, s[26:27]
	s_waitcnt lgkmcnt(0)
	v_add_f32_e32 v147, v177, v185
	v_mul_f32_e32 v148, v146, v147
	v_cmp_eq_u32_e32 vcc, s61, v251
	s_add_i32 s61, s61, 1
	s_nop 1
	v_cndmask_b32_e32 v250, v250, v148, vcc
	s_mov_b64 s[26:27], exec
	s_cmp_lt_u32 s61, 8
	s_cbranch_scc1 .LBB0_133
	s_mov_b32 s61, 0
	v_mov_b32_e32 v148, v250
	s_and_saveexec_b64 s[28:29], s[62:63]
	s_xor_b64 s[28:29], exec, s[28:29]
	s_cbranch_execz .LBB0_139
	v_mul_f32_e32 v146, 0xbfb8aa3b, v148
	v_rndne_f32_e32 v147, v146
	v_sub_f32_e32 v149, v146, v147
	v_fma_f32 v146, v148, s34, -v146
	v_fmac_f32_e32 v146, 0xb2a5705f, v148
	v_add_f32_e32 v146, v149, v146
	v_cvt_i32_f32_e32 v147, v147
	v_exp_f32_e32 v146, v146
	v_cmp_nlt_f32_e32 vcc, s35, v148
	v_ldexp_f32 v146, v146, v147
	s_nop 0
	v_cndmask_b32_e32 v146, 0, v146, vcc
	v_cmp_ngt_f32_e32 vcc, s36, v148
	s_nop 1
	v_cndmask_b32_e32 v146, v184, v146, vcc
	v_add_f32_e32 v146, 1.0, v146
	v_div_scale_f32 v147, s[30:31], v146, v146, 1.0
	v_rcp_f32_e32 v148, v147
	s_nop 0
	v_fma_f32 v149, -v147, v148, 1.0
	v_fmac_f32_e32 v148, v149, v148
	v_div_scale_f32 v149, vcc, 1.0, v146, 1.0
	v_mul_f32_e32 v150, v149, v148
	v_fma_f32 v151, -v147, v150, v149
	v_fmac_f32_e32 v150, v151, v148
	v_fma_f32 v147, -v147, v150, v149
	v_div_fmas_f32 v147, v147, v148, v150
	v_div_fixup_f32 v149, v147, v146, 1.0
